# P4 LoRA prefix item: fragment rows pulled into L1 by one batch of loads before the serialized fragment loads
# speedup vs baseline: 1.0052x; 1.0052x over previous
.LBB0_815:
	s_ashr_i32 s0, s10, 1
	s_mul_hi_i32 s1, s0, 0x7e07e07f
	s_lshr_b32 s6, s1, 31
	s_lshr_b32 s1, s1, 5
	s_add_i32 s1, s1, s6
	s_mulk_i32 s1, 0x1c0
	s_add_i32 s1, s1, s0
	s_lshl_b32 s67, s1, 4
	v_or_b32_e32 v78, s67, v169
	v_mad_i64_i32 v[102:103], s[0:1], v78, s56, v[118:119]
	global_load_dwordx4 v[244:247], v[102:103], off offset:3072
	global_load_dwordx4 v[244:247], v[102:103], off offset:3136
	global_load_dwordx4 v[244:247], v[102:103], off offset:3200
	global_load_dwordx4 v[244:247], v[102:103], off offset:3264
	global_load_dwordx4 v[244:247], v[102:103], off offset:3328
	global_load_dwordx4 v[244:247], v[102:103], off offset:3392
	global_load_dwordx4 v[244:247], v[102:103], off offset:3456
	global_load_dwordx4 v[244:247], v[102:103], off offset:3520
	global_load_dwordx4 v[244:247], v[102:103], off offset:3584
	global_load_dwordx4 v[244:247], v[102:103], off offset:-576
	global_load_dwordx4 v[244:247], v[102:103], off offset:-512
	global_load_dwordx4 v[244:247], v[102:103], off offset:-448
	global_load_dwordx4 v[244:247], v[102:103], off offset:-384
	global_load_dwordx4 v[244:247], v[102:103], off offset:-320
	global_load_dwordx4 v[244:247], v[102:103], off offset:-256
	global_load_dwordx4 v[244:247], v[102:103], off offset:-192
	global_load_dwordx4 v[244:247], v[102:103], off offset:-128
	global_load_dwordx4 v[244:247], v[102:103], off offset:-64
	global_load_dwordx4 v[74:77], v[102:103], off offset:3072
	v_mul_hi_i32 v79, v78, s35
	v_lshrrev_b32_e32 v80, 31, v79
	v_ashrrev_i32_e32 v79, 12, v79
	v_add_u32_e32 v79, v79, v80
	v_mul_i32_i24_e32 v79, 0x2010, v79
	v_sub_u32_e32 v78, v78, v79
	v_cmp_lt_i32_e32 vcc, 0, v78
	v_mov_b32_e32 v78, v111
	v_mov_b32_e32 v79, v111
	v_mov_b32_e32 v80, v111
	v_mov_b32_e32 v81, v111
	v_mov_b32_e32 v82, v111
	v_mov_b32_e32 v83, v111
	v_mov_b32_e32 v84, v111
	v_mov_b32_e32 v85, v111
	s_and_saveexec_b64 s[0:1], vcc
	s_cbranch_execz .LBB0_817
	global_load_dwordx4 v[86:89], v[102:103], off offset:-576
	s_waitcnt vmcnt(0)
	v_lshlrev_b32_e32 v85, 16, v86
	v_and_b32_e32 v84, 0xffff0000, v86
	v_lshlrev_b32_e32 v83, 16, v87
	v_and_b32_e32 v82, 0xffff0000, v87
	v_lshlrev_b32_e32 v81, 16, v88
	v_and_b32_e32 v80, 0xffff0000, v88
	v_lshlrev_b32_e32 v79, 16, v89
	v_and_b32_e32 v78, 0xffff0000, v89
